# static (slice,rank)=(bid&7,bid>>3) partition replaces per-phase XCC census (16 coherent loads + returning atomic) in down2/up/DSA_IN when grid==512
# speedup vs baseline: 1.0041x; 1.0041x over previous
; DI unsigned xb_ld(unsigned* p)              { return __hip_atomic_load(p, __ATOMIC_RELAXED, __HIP_MEMORY_SCOPE_AGENT); }
; DI unsigned xb_xcc_id() { return (unsigned)__builtin_amdgcn_s_getreg((3 << 11) | 20) & 0xFu; }
; DI void xcc_census(unsigned char* ws, u32* rankctr, int* sl, int tid) {
;   __syncthreads();
;   if (tid == 0) {
;     unsigned* bar = (unsigned*)(ws + OFF_BAR);
;     const unsigned myx = xb_xcc_id();
;     int nx = 0, xo = 0, nloc = 1;
;     for (unsigned j = 0; j < 16; ++j) { const unsigned cj = xb_ld(&bar[XB_XCNT(j)]); if (cj > 0u) { if (j == myx) { xo = nx; nloc = (int)cj; } ++nx; } }
;     sl[0] = (int)atomicAdd(rankctr + myx, 1u);
;     sl[1] = nloc; sl[2] = xo; sl[3] = nx;
;   }
;   __syncthreads();
; }
.LBB0_674:
	s_or_b64 exec, exec, s[8:9]
	v_mov_b32_e32 v4, v160
	s_waitcnt lgkmcnt(0)
	s_barrier
	s_getreg_b32 s4, hwreg(HW_REG_XCC_ID, 0, 4)
	v_cmp_eq_u32_e64 s[8:9], 0, v4
	s_barrier
	s_and_saveexec_b64 s[12:13], s[8:9]
	s_cbranch_execz .LBB0_678
	s_cmp_lg_u32 s26, 0x200
	s_cbranch_scc1 .Lmy_cen_0
	v_readlane_b32 s5, v255, 0
	s_lshr_b32 s6, s5, 3
	s_and_b32 s5, s5, 7
	v_mov_b32_e32 v6, s6
	v_mov_b32_e32 v7, 64
	v_mov_b32_e32 v8, s5
	v_mov_b32_e32 v9, 8
	v_mov_b32_e32 v0, 0
	ds_write_b128 v0, v[6:9] offset:16
	s_branch .LBB0_678
.Lmy_cen_0:
	v_mov_b32_e32 v0, 0x1c100000
	s_getreg_b32 s5, hwreg(HW_REG_XCC_ID, 0, 4)
	global_load_dword v18, v0, s[22:23] offset:1024 sc1
	global_load_dword v17, v0, s[22:23] offset:1280 sc1
	global_load_dword v16, v0, s[22:23] offset:1536 sc1
	global_load_dword v15, v0, s[22:23] offset:1792 sc1
	global_load_dword v14, v0, s[22:23] offset:2048 sc1
	global_load_dword v13, v0, s[22:23] offset:2304 sc1
	global_load_dword v12, v0, s[22:23] offset:2560 sc1
	global_load_dword v11, v0, s[22:23] offset:2816 sc1
	global_load_dword v10, v0, s[22:23] offset:3072 sc1
	global_load_dword v9, v0, s[22:23] offset:3328 sc1
	global_load_dword v8, v0, s[22:23] offset:3584 sc1
	global_load_dword v7, v0, s[22:23] offset:3840 sc1
	v_mov_b32_e32 v1, 0x1c101000
	global_load_dword v6, v1, s[22:23] sc1
	global_load_dword v5, v1, s[22:23] offset:256 sc1
	global_load_dword v2, v1, s[22:23] offset:512 sc1
	global_load_dword v0, v1, s[22:23] offset:768 sc1
	s_mov_b64 s[10:11], exec
	v_mbcnt_lo_u32_b32 v1, s10, 0
	v_mbcnt_hi_u32_b32 v1, s11, v1
	s_and_b32 s5, s5, 15
	v_cmp_eq_u32_e32 vcc, 0, v1
	s_and_saveexec_b64 s[14:15], vcc
	s_cbranch_execz .LBB0_677
	s_lshl_b32 s6, s5, 2
	s_add_u32 s6, s22, s6
	s_addc_u32 s7, s23, 0
	s_bcnt1_i32_b64 s10, s[10:11]
	v_bfrev_b32_e32 v3, 56
	v_mov_b32_e32 v19, s10
	global_atomic_add v3, v3, v19, s[6:7] offset:32 sc0

; DI unsigned xb_ld(unsigned* p)              { return __hip_atomic_load(p, __ATOMIC_RELAXED, __HIP_MEMORY_SCOPE_AGENT); }
; DI unsigned xb_xcc_id() { return (unsigned)__builtin_amdgcn_s_getreg((3 << 11) | 20) & 0xFu; }
; DI void xcc_census(unsigned char* ws, u32* rankctr, int* sl, int tid) {
;   __syncthreads();
;   if (tid == 0) {
;     unsigned* bar = (unsigned*)(ws + OFF_BAR);
;     const unsigned myx = xb_xcc_id();
;     int nx = 0, xo = 0, nloc = 1;
;     for (unsigned j = 0; j < 16; ++j) { const unsigned cj = xb_ld(&bar[XB_XCNT(j)]); if (cj > 0u) { if (j == myx) { xo = nx; nloc = (int)cj; } ++nx; } }
;     sl[0] = (int)atomicAdd(rankctr + myx, 1u);
;     sl[1] = nloc; sl[2] = xo; sl[3] = nx;
;   }
;   __syncthreads();
; }
.Lmy_cen_1:
	v_mov_b32_e32 v0, 0x1c100000
	s_getreg_b32 s5, hwreg(HW_REG_XCC_ID, 0, 4)
	global_load_dword v18, v0, s[22:23] offset:1024 sc1
	global_load_dword v17, v0, s[22:23] offset:1280 sc1
	global_load_dword v16, v0, s[22:23] offset:1536 sc1
	global_load_dword v15, v0, s[22:23] offset:1792 sc1
	global_load_dword v14, v0, s[22:23] offset:2048 sc1
	global_load_dword v13, v0, s[22:23] offset:2304 sc1
	global_load_dword v12, v0, s[22:23] offset:2560 sc1
	global_load_dword v11, v0, s[22:23] offset:2816 sc1
	global_load_dword v10, v0, s[22:23] offset:3072 sc1
	global_load_dword v9, v0, s[22:23] offset:3328 sc1
	global_load_dword v8, v0, s[22:23] offset:3584 sc1
	global_load_dword v7, v0, s[22:23] offset:3840 sc1
	v_mov_b32_e32 v1, 0x1c101000
	global_load_dword v6, v1, s[22:23] sc1
	global_load_dword v5, v1, s[22:23] offset:256 sc1
	global_load_dword v2, v1, s[22:23] offset:512 sc1
	global_load_dword v0, v1, s[22:23] offset:768 sc1
	s_mov_b64 s[10:11], exec
	v_mbcnt_lo_u32_b32 v1, s10, 0
	v_mbcnt_hi_u32_b32 v1, s11, v1
	s_and_b32 s5, s5, 15
	v_cmp_eq_u32_e32 vcc, 0, v1
	s_and_saveexec_b64 s[14:15], vcc
	s_cbranch_execz .LBB0_810
	s_lshl_b32 s6, s5, 2
	s_add_u32 s6, s22, s6
	s_addc_u32 s7, s23, 0
	s_bcnt1_i32_b64 s10, s[10:11]
	v_bfrev_b32_e32 v3, 56
	v_mov_b32_e32 v19, s10
	global_atomic_add v3, v3, v19, s[6:7] offset:160 sc0

; DI unsigned xb_ld(unsigned* p)              { return __hip_atomic_load(p, __ATOMIC_RELAXED, __HIP_MEMORY_SCOPE_AGENT); }
; DI unsigned xb_xcc_id() { return (unsigned)__builtin_amdgcn_s_getreg((3 << 11) | 20) & 0xFu; }
;     ...
;   if constexpr (EPI == EPI_DSA_IN) {
;     int* sl = (int*)(smem + 40960);
;     __syncthreads();
;     if (tid == 0) {
;       unsigned* bar = (unsigned*)(ws + OFF_BAR);
;       const unsigned myx = xb_xcc_id();
;       int nx = 0, xo = 0, nloc = 1;
;       for (unsigned j = 0; j < 16; ++j) { const unsigned cj = xb_ld(&bar[XB_XCNT(j)]); if (cj > 0u) { if (j == myx) { xo = nx; nloc = (int)cj; } ++nx; } }
;       sl[0] = (int)atomicAdd((u32*)(ws + OFF_CTR) + 128 + myx, 1u);
;       sl[1] = nloc; sl[2] = xo; sl[3] = nx;
;     }
;     __syncthreads();
;     if (sl[3] == 8) {
;       xi = sl[2];
;       cntS = (Ntiles - 1 - xi) / 8 + 1;
;       t_start = sl[0]; t_step = sl[1]; t_total = 128 * cntS;
;     }
;     __syncthreads();
;   }
.LBB0_936:
	s_or_b64 exec, exec, s[8:9]
	s_waitcnt lgkmcnt(0)
	v_mov_b32_e32 v0, v160
	s_barrier
	s_nop 0
	v_cmp_eq_u32_e32 vcc, 0, v0
	s_barrier
	s_and_saveexec_b64 s[10:11], vcc
	s_cbranch_execz .LBB0_940
	s_cmp_lg_u32 s26, 0x200
	s_cbranch_scc1 .Lmy_cen_2
	v_readlane_b32 s4, v255, 0
	s_lshr_b32 s5, s4, 3
	s_and_b32 s4, s4, 7
	v_mov_b32_e32 v4, s5
	v_mov_b32_e32 v5, 64
	v_mov_b32_e32 v6, s4
	v_mov_b32_e32 v7, 8
	v_mov_b32_e32 v1, 0
	ds_write_b128 v1, v[4:7] offset:40960
	s_branch .LBB0_940
.Lmy_cen_2:
	v_mov_b32_e32 v1, 0x1c100000
	s_getreg_b32 s4, hwreg(HW_REG_XCC_ID, 0, 4)
	global_load_dword v18, v1, s[22:23] offset:1024 sc1
	global_load_dword v17, v1, s[22:23] offset:1280 sc1
	global_load_dword v16, v1, s[22:23] offset:1536 sc1
	global_load_dword v15, v1, s[22:23] offset:1792 sc1
	global_load_dword v14, v1, s[22:23] offset:2048 sc1
	global_load_dword v13, v1, s[22:23] offset:2304 sc1
	global_load_dword v12, v1, s[22:23] offset:2560 sc1
	global_load_dword v11, v1, s[22:23] offset:2816 sc1
	global_load_dword v10, v1, s[22:23] offset:3072 sc1
	global_load_dword v9, v1, s[22:23] offset:3328 sc1
	global_load_dword v8, v1, s[22:23] offset:3584 sc1
	global_load_dword v7, v1, s[22:23] offset:3840 sc1
	v_mov_b32_e32 v2, 0x1c101000
	global_load_dword v6, v2, s[22:23] sc1
	global_load_dword v5, v2, s[22:23] offset:256 sc1
	global_load_dword v3, v2, s[22:23] offset:512 sc1
	global_load_dword v1, v2, s[22:23] offset:768 sc1
	s_mov_b64 s[8:9], exec
	v_mbcnt_lo_u32_b32 v2, s8, 0
	v_mbcnt_hi_u32_b32 v2, s9, v2
	s_and_b32 s4, s4, 15
	v_cmp_eq_u32_e32 vcc, 0, v2
	s_and_saveexec_b64 s[12:13], vcc
	s_cbranch_execz .LBB0_939
	s_lshl_b32 s5, s4, 2
	s_add_u32 s6, s22, s5
	s_addc_u32 s7, s23, 0
	s_bcnt1_i32_b64 s5, s[8:9]
	v_bfrev_b32_e32 v4, 56
	v_mov_b32_e32 v19, s5
	global_atomic_add v4, v4, v19, s[6:7] offset:512 sc0

; DI unsigned xb_ld(unsigned* p)              { return __hip_atomic_load(p, __ATOMIC_RELAXED, __HIP_MEMORY_SCOPE_AGENT); }
; DI unsigned xb_xcc_id() { return (unsigned)__builtin_amdgcn_s_getreg((3 << 11) | 20) & 0xFu; }
; DI void xcc_census(unsigned char* ws, u32* rankctr, int* sl, int tid) {
;   __syncthreads();
;   if (tid == 0) {
;     unsigned* bar = (unsigned*)(ws + OFF_BAR);
;     const unsigned myx = xb_xcc_id();
;     int nx = 0, xo = 0, nloc = 1;
;     for (unsigned j = 0; j < 16; ++j) { const unsigned cj = xb_ld(&bar[XB_XCNT(j)]); if (cj > 0u) { if (j == myx) { xo = nx; nloc = (int)cj; } ++nx; } }
;     sl[0] = (int)atomicAdd(rankctr + myx, 1u);
;     sl[1] = nloc; sl[2] = xo; sl[3] = nx;
;   }
;   __syncthreads();
; }
.LBB0_1497:
	s_or_b64 exec, exec, s[6:7]
	v_mov_b32_e32 v4, v160
	s_waitcnt lgkmcnt(0)
	s_barrier
	s_getreg_b32 s4, hwreg(HW_REG_XCC_ID, 0, 4)
	v_cmp_eq_u32_e64 s[6:7], 0, v4
	s_barrier
	s_and_saveexec_b64 s[10:11], s[6:7]
	s_cbranch_execz .LBB0_1501
	s_cmp_lg_u32 s26, 0x200
	s_cbranch_scc1 .Lmy_cen_3
	v_readlane_b32 s0, v255, 0
	s_lshr_b32 s1, s0, 3
	s_and_b32 s0, s0, 7
	v_mov_b32_e32 v6, s1
	v_mov_b32_e32 v7, 64
	v_mov_b32_e32 v8, s0
	v_mov_b32_e32 v9, 8
	v_mov_b32_e32 v0, 0
	ds_write_b128 v0, v[6:9] offset:16
	s_branch .LBB0_1501
.Lmy_cen_3:
	v_mov_b32_e32 v0, 0x1c100000
	s_getreg_b32 s0, hwreg(HW_REG_XCC_ID, 0, 4)
	global_load_dword v18, v0, s[22:23] offset:1024 sc1
	global_load_dword v17, v0, s[22:23] offset:1280 sc1
	global_load_dword v16, v0, s[22:23] offset:1536 sc1
	global_load_dword v15, v0, s[22:23] offset:1792 sc1
	global_load_dword v14, v0, s[22:23] offset:2048 sc1
	global_load_dword v13, v0, s[22:23] offset:2304 sc1
	global_load_dword v12, v0, s[22:23] offset:2560 sc1
	global_load_dword v11, v0, s[22:23] offset:2816 sc1
	global_load_dword v10, v0, s[22:23] offset:3072 sc1
	global_load_dword v9, v0, s[22:23] offset:3328 sc1
	global_load_dword v8, v0, s[22:23] offset:3584 sc1
	global_load_dword v7, v0, s[22:23] offset:3840 sc1
	v_mov_b32_e32 v1, 0x1c101000
	global_load_dword v6, v1, s[22:23] sc1
	global_load_dword v5, v1, s[22:23] offset:256 sc1
	global_load_dword v2, v1, s[22:23] offset:512 sc1
	global_load_dword v0, v1, s[22:23] offset:768 sc1
	s_mov_b64 s[8:9], exec
	v_mbcnt_lo_u32_b32 v1, s8, 0
	v_mbcnt_hi_u32_b32 v1, s9, v1
	s_and_b32 s0, s0, 15
	v_cmp_eq_u32_e32 vcc, 0, v1
	s_and_saveexec_b64 s[12:13], vcc
	s_cbranch_execz .LBB0_1500
	s_lshl_b32 s1, s0, 2
	s_add_u32 s14, s22, s1
	s_addc_u32 s15, s23, 0
	s_bcnt1_i32_b64 s1, s[8:9]
	v_bfrev_b32_e32 v3, 56
	v_mov_b32_e32 v19, s1
	global_atomic_add v3, v3, v19, s[14:15] offset:288 sc0

; DI unsigned xb_ld(unsigned* p)              { return __hip_atomic_load(p, __ATOMIC_RELAXED, __HIP_MEMORY_SCOPE_AGENT); }
; DI unsigned xb_xcc_id() { return (unsigned)__builtin_amdgcn_s_getreg((3 << 11) | 20) & 0xFu; }
; DI void xcc_census(unsigned char* ws, u32* rankctr, int* sl, int tid) {
;   __syncthreads();
;   if (tid == 0) {
;     unsigned* bar = (unsigned*)(ws + OFF_BAR);
;     const unsigned myx = xb_xcc_id();
;     int nx = 0, xo = 0, nloc = 1;
;     for (unsigned j = 0; j < 16; ++j) { const unsigned cj = xb_ld(&bar[XB_XCNT(j)]); if (cj > 0u) { if (j == myx) { xo = nx; nloc = (int)cj; } ++nx; } }
;     sl[0] = (int)atomicAdd(rankctr + myx, 1u);
;     sl[1] = nloc; sl[2] = xo; sl[3] = nx;
;   }
;   __syncthreads();
; }
; DI void peer_up_phase(const Params& p, unsigned char* smem, int layer, u32* ctr) {
;     ...
;   xcc_census(ws, ctr + 8, slot + 4, tid);
;   const bool stat = (slot[7] == 8);
;   int it_next = slot[4];
;   const int it_step = slot[5], xi = slot[6];
.LBB0_1630:
	s_or_b64 exec, exec, s[2:3]
	v_mov_b32_e32 v4, v160
	s_waitcnt lgkmcnt(0)
	s_barrier
	s_getreg_b32 s4, hwreg(HW_REG_XCC_ID, 0, 4)
	v_cmp_eq_u32_e64 s[2:3], 0, v4
	s_barrier
	s_and_saveexec_b64 s[8:9], s[2:3]
	s_cbranch_execz .LBB0_1634
	s_cmp_lg_u32 s26, 0x200
	s_cbranch_scc1 .Lmy_cen_4
	v_readlane_b32 s0, v255, 0
	s_lshr_b32 s1, s0, 3
	s_and_b32 s0, s0, 7
	v_mov_b32_e32 v6, s1
	v_mov_b32_e32 v7, 64
	v_mov_b32_e32 v8, s0
	v_mov_b32_e32 v9, 8
	v_mov_b32_e32 v0, 0
	ds_write_b128 v0, v[6:9] offset:16
	s_branch .LBB0_1634
.Lmy_cen_4:
	v_mov_b32_e32 v0, 0x1c100000
	s_getreg_b32 s0, hwreg(HW_REG_XCC_ID, 0, 4)
	global_load_dword v18, v0, s[22:23] offset:1024 sc1
	global_load_dword v17, v0, s[22:23] offset:1280 sc1
	global_load_dword v16, v0, s[22:23] offset:1536 sc1
	global_load_dword v15, v0, s[22:23] offset:1792 sc1
	global_load_dword v14, v0, s[22:23] offset:2048 sc1
	global_load_dword v13, v0, s[22:23] offset:2304 sc1
	global_load_dword v12, v0, s[22:23] offset:2560 sc1
	global_load_dword v11, v0, s[22:23] offset:2816 sc1
	global_load_dword v10, v0, s[22:23] offset:3072 sc1
	global_load_dword v9, v0, s[22:23] offset:3328 sc1
	global_load_dword v8, v0, s[22:23] offset:3584 sc1
	global_load_dword v7, v0, s[22:23] offset:3840 sc1
	v_mov_b32_e32 v1, 0x1c101000
	global_load_dword v6, v1, s[22:23] sc1
	global_load_dword v5, v1, s[22:23] offset:256 sc1
	global_load_dword v2, v1, s[22:23] offset:512 sc1
	global_load_dword v0, v1, s[22:23] offset:768 sc1
	s_mov_b64 s[6:7], exec
	v_mbcnt_lo_u32_b32 v1, s6, 0
	v_mbcnt_hi_u32_b32 v1, s7, v1
	s_and_b32 s0, s0, 15
	v_cmp_eq_u32_e32 vcc, 0, v1
	s_and_saveexec_b64 s[10:11], vcc
	s_cbranch_execz .LBB0_1633
	s_lshl_b32 s1, s0, 2
	s_add_u32 s12, s22, s1
	s_addc_u32 s13, s23, 0
	s_bcnt1_i32_b64 s1, s[6:7]
	v_bfrev_b32_e32 v3, 56
	v_mov_b32_e32 v19, s1
	global_atomic_add v3, v3, v19, s[12:13] offset:416 sc0
